# loop-edge edit: s_sleep removed from the grid-barrier arrival-counter poll loops
# speedup vs baseline: 1.0046x; 1.0046x over previous
; __device__ __forceinline__ unsigned xb_ld(unsigned* p)              { return __hip_atomic_load(p, __ATOMIC_RELAXED, __HIP_MEMORY_SCOPE_AGENT); }
; #define XB_SPIN(cond, bar) do { unsigned _sp = 0; while (cond) { __builtin_amdgcn_s_sleep(1); \
;     if ((++_sp & 255u) == 0u) { if (xb_ld(&(bar)[XB_TMO])) break; if (_sp > XB_SPIN_CAP) { atomicAdd(&(bar)[XB_TMO], 1u); break; } } } } while (0)
; __device__ __forceinline__ void xcd_barrier(const XcdBarrier& b) {
;     ...
;             XB_SPIN(xb_ld(&bar[XB_XGEN(b.x)]) == gen, bar);
.Lcg_247:
	s_and_b32 s1, s0, 0xff
	s_mov_b64 s[26:27], -1
	s_cmp_lg_u32 s1, 0
	s_mov_b64 s[40:41], -1
	s_nop 0
	s_cbranch_scc0 .Lcg_250
	s_and_b64 vcc, exec, s[40:41]
	s_cbranch_vccz .Lcg_246

; __device__ __forceinline__ unsigned xb_ld(unsigned* p)              { return __hip_atomic_load(p, __ATOMIC_RELAXED, __HIP_MEMORY_SCOPE_AGENT); }
; #define XB_SPIN(cond, bar) do { unsigned _sp = 0; while (cond) { __builtin_amdgcn_s_sleep(1); \
;     if ((++_sp & 255u) == 0u) { if (xb_ld(&(bar)[XB_TMO])) break; if (_sp > XB_SPIN_CAP) { atomicAdd(&(bar)[XB_TMO], 1u); break; } } } } while (0)
; __device__ __forceinline__ void xcd_barrier(const XcdBarrier& b) {
;     ...
;             XB_SPIN(xb_ld(&bar[XB_XGEN(b.x)]) == gen, bar);
.LBB0_345:
	s_and_b32 s1, s0, 0xff
	s_mov_b64 s[38:39], -1
	s_cmp_lg_u32 s1, 0
	s_mov_b64 s[42:43], -1
	s_nop 0
	s_cbranch_scc0 .LBB0_348
	s_and_b64 vcc, exec, s[42:43]
	s_cbranch_vccz .LBB0_344

; __device__ __forceinline__ unsigned xb_ld(unsigned* p)              { return __hip_atomic_load(p, __ATOMIC_RELAXED, __HIP_MEMORY_SCOPE_AGENT); }
; #define XB_SPIN(cond, bar) do { unsigned _sp = 0; while (cond) { __builtin_amdgcn_s_sleep(1); \
;     if ((++_sp & 255u) == 0u) { if (xb_ld(&(bar)[XB_TMO])) break; if (_sp > XB_SPIN_CAP) { atomicAdd(&(bar)[XB_TMO], 1u); break; } } } } while (0)
; __device__ __forceinline__ void xcd_barrier(const XcdBarrier& b) {
;     ...
;             XB_SPIN(xb_ld(&bar[XB_XGEN(b.x)]) == gen, bar);
.LBB0_679:
	s_and_b32 s1, s0, 0xff
	s_mov_b64 s[34:35], -1
	s_cmp_lg_u32 s1, 0
	s_mov_b64 s[38:39], -1
	s_nop 0
	s_cbranch_scc0 .LBB0_682
	s_and_b64 vcc, exec, s[38:39]
	s_cbranch_vccz .LBB0_678

; __device__ __forceinline__ unsigned xb_ld(unsigned* p)              { return __hip_atomic_load(p, __ATOMIC_RELAXED, __HIP_MEMORY_SCOPE_AGENT); }
; #define XB_SPIN(cond, bar) do { unsigned _sp = 0; while (cond) { __builtin_amdgcn_s_sleep(1); \
;     if ((++_sp & 255u) == 0u) { if (xb_ld(&(bar)[XB_TMO])) break; if (_sp > XB_SPIN_CAP) { atomicAdd(&(bar)[XB_TMO], 1u); break; } } } } while (0)
; __device__ __forceinline__ void xcd_barrier(const XcdBarrier& b) {
;     ...
;             XB_SPIN(xb_ld(&bar[XB_XGEN(b.x)]) == gen, bar);
.LBB0_782:
	s_and_b32 s1, s0, 0xff
	s_mov_b64 s[30:31], -1
	s_cmp_lg_u32 s1, 0
	s_mov_b64 s[36:37], -1
	s_nop 0
	s_cbranch_scc0 .LBB0_785
	s_and_b64 vcc, exec, s[36:37]
	s_cbranch_vccz .LBB0_781

; __device__ __forceinline__ unsigned xb_ld(unsigned* p)              { return __hip_atomic_load(p, __ATOMIC_RELAXED, __HIP_MEMORY_SCOPE_AGENT); }
; #define XB_SPIN(cond, bar) do { unsigned _sp = 0; while (cond) { __builtin_amdgcn_s_sleep(1); \
;     if ((++_sp & 255u) == 0u) { if (xb_ld(&(bar)[XB_TMO])) break; if (_sp > XB_SPIN_CAP) { atomicAdd(&(bar)[XB_TMO], 1u); break; } } } } while (0)
; __device__ __forceinline__ void xcd_barrier(const XcdBarrier& b) {
;     ...
;             XB_SPIN(xb_ld(&bar[XB_XGEN(b.x)]) == gen, bar);
.LBB0_1187:
	s_and_b32 s1, s0, 0xff
	s_mov_b64 s[26:27], -1
	s_cmp_lg_u32 s1, 0
	s_mov_b64 s[30:31], -1
	s_nop 0
	s_cbranch_scc0 .LBB0_1190
	s_and_b64 vcc, exec, s[30:31]
	s_cbranch_vccz .LBB0_1186

; __device__ __forceinline__ unsigned xb_ld(unsigned* p)              { return __hip_atomic_load(p, __ATOMIC_RELAXED, __HIP_MEMORY_SCOPE_AGENT); }
; #define XB_SPIN(cond, bar) do { unsigned _sp = 0; while (cond) { __builtin_amdgcn_s_sleep(1); \
;     if ((++_sp & 255u) == 0u) { if (xb_ld(&(bar)[XB_TMO])) break; if (_sp > XB_SPIN_CAP) { atomicAdd(&(bar)[XB_TMO], 1u); break; } } } } while (0)
; __device__ __forceinline__ void xcd_barrier(const XcdBarrier& b) {
;     ...
;             XB_SPIN(xb_ld(&bar[XB_XGEN(b.x)]) == gen, bar);
.LBB0_1482:
	s_and_b32 s1, s0, 0xff
	s_mov_b64 s[24:25], -1
	s_cmp_lg_u32 s1, 0
	s_mov_b64 s[28:29], -1
	s_nop 0
	s_cbranch_scc0 .LBB0_1485
	s_and_b64 vcc, exec, s[28:29]
	s_cbranch_vccz .LBB0_1481
